# beta/alpha MFMA GEMV: the four weight-piece loads are issued before the entry barrier (single accumulator as in v143)
# baseline (speedup 1.0000x reference)
; __device__ __forceinline__ float bf2f(bfu h) { return __uint_as_float(((unsigned)h) << 16); }
; #define SHX(v, m) shx_((v), (m), lane)
; __device__ __forceinline__ int ptid_(int wave) { int l_; asm volatile("v_mbcnt_lo_u32_b32 %0, -1, 0\n\tv_mbcnt_hi_u32_b32 %0, -1, %0" : "=v"(l_)); return (wave << 6) | l_; }
; __device__ void ba_item(const Params& p, int L, int rp) {
;   const float* misc = (const float*)(p.ws + MISC_OFF);
;   float* miscw = (float*)(p.ws + MISC_OFF);
;   const bfu* hb = (const bfu*)(p.ws + HB_OFF);
;   const float* wba = misc + MF_WBA + (L >> 1) * 8192;
;   const float* rowss = misc + MF_RSP + (L == 0 ? 0L : 2L * MTOK * 16);
;   int tid = ptid_(p.tid); asm volatile("" : "+v"(tid));
;   const int wid = tid >> 6, lane = tid & 63;
;   f32x4 wr_[8][4];
;   _Pragma("unroll") for (int j = 0; j < 8; ++j) _Pragma("unroll") for (int e4 = 0; e4 < 4; ++e4)
;     wr_[j][e4] = *(const f32x4*)(wba + j * 1024 + lane * 16 + e4 * 4);
;   for (int bt = 0; bt < 8; ++bt) {
;     bf16x8 h0[2], h1[2]; f32x4 ps[2][4];
;     _Pragma("unroll") for (int u = 0; u < 2; ++u) {
;       const int row = rp * 128 + wid * 16 + bt * 2 + u;
;       const bfu* hr = hb + (long)row * 1024 + lane * 16;
;       h0[u] = *(const bf16x8*)hr; h1[u] = *(const bf16x8*)(hr + 8);
;       _Pragma("unroll") for (int i = 0; i < 4; ++i) ps[u][i] = *(const f32x4*)(rowss + (long)row * 16 + i * 4);
;     }
;     _Pragma("unroll") for (int u = 0; u < 2; ++u) {
;       const int row = rp * 128 + wid * 16 + bt * 2 + u;
;       float hf[16];
;       _Pragma("unroll") for (int e = 0; e < 8; ++e) { hf[e] = bf2f((bfu)h0[u][e]); hf[8 + e] = bf2f((bfu)h1[u][e]); }
;       float a[8];
;       _Pragma("unroll") for (int j = 0; j < 8; ++j) {
;         float s = 0.f;
;         _Pragma("unroll") for (int e4 = 0; e4 < 4; ++e4) _Pragma("unroll") for (int e = 0; e < 4; ++e) s += hf[e4 * 4 + e] * wr_[j][e4][e];
;         _Pragma("unroll") for (int o = 32; o >= 1; o >>= 1) s += SHX(s, o);
;         a[j] = s;
;       }
.LBB0_612:
	s_cmpk_gt_i32 s18, 0x6ff
	s_mov_b64 s[0:1], -1
	s_cbranch_scc0 .LBB0_628
	v_mbcnt_lo_u32_b32 v0, -1, 0
	v_mbcnt_hi_u32_b32 v0, -1, v0
	s_waitcnt vmcnt(0) lgkmcnt(0)
	v_or_b32_e32 v144, s33, v0
	v_lshlrev_b32_e32 v150, 4, v144
	global_load_dwordx4 v[152:155], v150, s[26:27]
	v_add_u32_e32 v150, 0x2000, v150
	global_load_dwordx4 v[156:159], v150, s[26:27]
	v_add_u32_e32 v150, 0x2000, v150
	global_load_dwordx4 v[160:163], v150, s[26:27]
	v_add_u32_e32 v150, 0x2000, v150
	global_load_dwordx4 v[164:167], v150, s[26:27]
	s_barrier
	v_readlane_b32 s24, v254, 62
	v_readlane_b32 s25, v254, 63
	s_lshr_b32 s2, s33, 2
	s_add_i32 s2, s2, s20
	s_add_i32 s2, s2, 0xfffc8000
	v_and_b32_e32 v2, 15, v0
	v_lshrrev_b32_e32 v3, 4, v0
	v_and_b32_e32 v145, 0xff, v144
	v_lshrrev_b32_e32 v149, 3, v145
	v_lshlrev_b32_e32 v149, 10, v149
	v_bfe_u32 v146, v144, 1, 2
	v_lshl_or_b32 v149, v146, 8, v149
	v_lshrrev_b32_e32 v146, 8, v144
	v_lshl_or_b32 v149, v146, 5, v149
	v_and_b32_e32 v146, 1, v144
	v_lshl_or_b32 v149, v146, 4, v149
	v_add_u32_e32 v144, s2, v2
	v_lshlrev_b32_e32 v144, 11, v144
	v_lshl_add_u32 v144, v3, 4, v144
	v_mov_b32_e32 v145, 0
	v_lshl_add_u64 v[4:5], s[80:81], 0, v[144:145]
	v_and_b32_e32 v138, 7, v2
	v_lshlrev_b32_e32 v148, 5, v138
	v_lshl_or_b32 v148, v3, 8, v148
	v_lshl_add_u32 v144, v3, 2, s2
	v_lshlrev_b32_e32 v144, 6, v144
	v_lshl_add_u64 v[136:137], s[24:25], 0, v[144:145]
	v_max_u32_e32 v144, 4, v138
	v_add_u32_e32 v144, s19, v144
	v_lshlrev_b32_e32 v144, 2, v144
	v_readlane_b32 s92, v254, 0
	v_readlane_b32 s93, v254, 1
	v_readlane_b32 s94, v254, 2
	v_readlane_b32 s95, v254, 3
	v_readlane_b32 s0, v252, 18
	v_readlane_b32 s1, v252, 19
	v_lshl_add_u32 v146, v3, 2, s2
	v_lshlrev_b32_e32 v146, 5, v146
	v_lshl_add_u32 v146, v138, 2, v146
	v_mov_b32_e32 v147, 0
	v_lshl_add_u64 v[140:141], s[0:1], 0, v[146:147]
	global_load_dword v142, v144, s[94:95]
	global_load_dword v143, v144, s[92:93]
	global_load_dwordx4 v[72:75], v[136:137], off offset:0
	global_load_dwordx4 v[76:79], v[136:137], off offset:16
	global_load_dwordx4 v[80:83], v[136:137], off offset:32
	global_load_dwordx4 v[84:87], v[136:137], off offset:48
	global_load_dwordx4 v[88:91], v[136:137], off offset:64
	global_load_dwordx4 v[92:95], v[136:137], off offset:80
	global_load_dwordx4 v[96:99], v[136:137], off offset:96
	global_load_dwordx4 v[100:103], v[136:137], off offset:112
	global_load_dwordx4 v[104:107], v[136:137], off offset:128
	global_load_dwordx4 v[108:111], v[136:137], off offset:144
	global_load_dwordx4 v[112:115], v[136:137], off offset:160
	global_load_dwordx4 v[116:119], v[136:137], off offset:176
	global_load_dwordx4 v[120:123], v[136:137], off offset:192
	global_load_dwordx4 v[124:127], v[136:137], off offset:208
	global_load_dwordx4 v[128:131], v[136:137], off offset:224
	global_load_dwordx4 v[132:135], v[136:137], off offset:240
	v_mov_b32_e32 v8, 0
	v_mov_b32_e32 v9, 0
	v_mov_b32_e32 v10, 0
	v_mov_b32_e32 v11, 0
	v_mov_b32_e32 v12, 0
	v_mov_b32_e32 v13, 0
	v_mov_b32_e32 v14, 0
	v_mov_b32_e32 v15, 0
	global_load_dwordx4 v[16:19], v[4:5], off
	global_load_dwordx4 v[20:23], v[4:5], off offset:64
	global_load_dwordx4 v[24:27], v[4:5], off offset:128
	global_load_dwordx4 v[28:31], v[4:5], off offset:192
	global_load_dwordx4 v[32:35], v[4:5], off offset:256
	global_load_dwordx4 v[36:39], v[4:5], off offset:320
	global_load_dwordx4 v[40:43], v[4:5], off offset:384
	global_load_dwordx4 v[44:47], v[4:5], off offset:448
	s_waitcnt vmcnt(26)
	ds_write_b128 v149, v[152:155]
	ds_write_b128 v149, v[156:159] offset:64
	ds_write_b128 v149, v[160:163] offset:128
	ds_write_b128 v149, v[164:167] offset:192
	s_waitcnt lgkmcnt(0)
	s_barrier
	ds_read_b128 v[48:51], v148
	ds_read_b128 v[52:55], v148 offset:16
	ds_read_b128 v[56:59], v148 offset:1024
	ds_read_b128 v[60:63], v148 offset:1040
	s_waitcnt vmcnt(7)
	v_lshlrev_b32_e32 v64, 16, v16
	v_and_b32_e32 v65, 0xffff0000, v16
	v_lshlrev_b32_e32 v66, 16, v17
	v_and_b32_e32 v67, 0xffff0000, v17
	v_lshlrev_b32_e32 v68, 16, v18
	v_and_b32_e32 v69, 0xffff0000, v18
	v_lshlrev_b32_e32 v70, 16, v19
	v_and_b32_e32 v71, 0xffff0000, v19
	s_waitcnt lgkmcnt(2)
	v_mfma_f32_16x16x4_f32 v[8:11], v64, v48, v[8:11]
	v_mfma_f32_16x16x4_f32 v[8:11], v65, v49, v[8:11]
	v_mfma_f32_16x16x4_f32 v[8:11], v66, v50, v[8:11]
	v_mfma_f32_16x16x4_f32 v[8:11], v67, v51, v[8:11]
	v_mfma_f32_16x16x4_f32 v[8:11], v68, v52, v[8:11]
	v_mfma_f32_16x16x4_f32 v[8:11], v69, v53, v[8:11]
	v_mfma_f32_16x16x4_f32 v[8:11], v70, v54, v[8:11]
	v_mfma_f32_16x16x4_f32 v[8:11], v71, v55, v[8:11]
	global_load_dwordx4 v[16:19], v[4:5], off offset:512
	ds_read_b128 v[48:51], v148 offset:2048
	ds_read_b128 v[52:55], v148 offset:2064
	s_waitcnt vmcnt(7)
	v_lshlrev_b32_e32 v64, 16, v20
	v_and_b32_e32 v65, 0xffff0000, v20
	v_lshlrev_b32_e32 v66, 16, v21
	v_and_b32_e32 v67, 0xffff0000, v21
	v_lshlrev_b32_e32 v68, 16, v22
	v_and_b32_e32 v69, 0xffff0000, v22
	v_lshlrev_b32_e32 v70, 16, v23
	v_and_b32_e32 v71, 0xffff0000, v23
	s_waitcnt lgkmcnt(2)
	v_mfma_f32_16x16x4_f32 v[8:11], v64, v56, v[8:11]
	v_mfma_f32_16x16x4_f32 v[8:11], v65, v57, v[8:11]
	v_mfma_f32_16x16x4_f32 v[8:11], v66, v58, v[8:11]
	v_mfma_f32_16x16x4_f32 v[8:11], v67, v59, v[8:11]
	v_mfma_f32_16x16x4_f32 v[8:11], v68, v60, v[8:11]
	v_mfma_f32_16x16x4_f32 v[8:11], v69, v61, v[8:11]
	v_mfma_f32_16x16x4_f32 v[8:11], v70, v62, v[8:11]
	v_mfma_f32_16x16x4_f32 v[8:11], v71, v63, v[8:11]
	global_load_dwordx4 v[20:23], v[4:5], off offset:576
	ds_read_b128 v[56:59], v148 offset:3072
	ds_read_b128 v[60:63], v148 offset:3088
	s_waitcnt vmcnt(7)
; __device__ __forceinline__ float bf2f(bfu h) { return __uint_as_float(((unsigned)h) << 16); }
; #define SHX(v, m) shx_((v), (m), lane)
; __device__ void ba_item(const Params& p, int L, int rp) {
;     ...
;       _Pragma("unroll") for (int e = 0; e < 8; ++e) { hf[e] = bf2f((bfu)h0[u][e]); hf[8 + e] = bf2f((bfu)h1[u][e]); }
;       float a[8];
;       _Pragma("unroll") for (int j = 0; j < 8; ++j) {
;         float s = 0.f;
;         _Pragma("unroll") for (int e4 = 0; e4 < 4; ++e4) _Pragma("unroll") for (int e = 0; e < 4; ++e) s += hf[e4 * 4 + e] * wr_[j][e4][e];
;         _Pragma("unroll") for (int o = 32; o >= 1; o >>= 1) s += SHX(s, o);
;         a[j] = s;
;       }
	v_lshlrev_b32_e32 v64, 16, v24
	v_and_b32_e32 v65, 0xffff0000, v24
	v_lshlrev_b32_e32 v66, 16, v25
	v_and_b32_e32 v67, 0xffff0000, v25
	v_lshlrev_b32_e32 v68, 16, v26
	v_and_b32_e32 v69, 0xffff0000, v26
	v_lshlrev_b32_e32 v70, 16, v27
	v_and_b32_e32 v71, 0xffff0000, v27
	s_waitcnt lgkmcnt(2)
	v_mfma_f32_16x16x4_f32 v[8:11], v64, v48, v[8:11]
	v_mfma_f32_16x16x4_f32 v[8:11], v65, v49, v[8:11]
	v_mfma_f32_16x16x4_f32 v[8:11], v66, v50, v[8:11]
	v_mfma_f32_16x16x4_f32 v[8:11], v67, v51, v[8:11]
	v_mfma_f32_16x16x4_f32 v[8:11], v68, v52, v[8:11]
	v_mfma_f32_16x16x4_f32 v[8:11], v69, v53, v[8:11]
	v_mfma_f32_16x16x4_f32 v[8:11], v70, v54, v[8:11]
	v_mfma_f32_16x16x4_f32 v[8:11], v71, v55, v[8:11]
	global_load_dwordx4 v[24:27], v[4:5], off offset:640
	ds_read_b128 v[48:51], v148 offset:4096
	ds_read_b128 v[52:55], v148 offset:4112
	s_waitcnt vmcnt(7)
	v_lshlrev_b32_e32 v64, 16, v28
	v_and_b32_e32 v65, 0xffff0000, v28
	v_lshlrev_b32_e32 v66, 16, v29
	v_and_b32_e32 v67, 0xffff0000, v29
	v_lshlrev_b32_e32 v68, 16, v30
	v_and_b32_e32 v69, 0xffff0000, v30
	v_lshlrev_b32_e32 v70, 16, v31
	v_and_b32_e32 v71, 0xffff0000, v31
	s_waitcnt lgkmcnt(2)
	v_mfma_f32_16x16x4_f32 v[8:11], v64, v56, v[8:11]
	v_mfma_f32_16x16x4_f32 v[8:11], v65, v57, v[8:11]
	v_mfma_f32_16x16x4_f32 v[8:11], v66, v58, v[8:11]
	v_mfma_f32_16x16x4_f32 v[8:11], v67, v59, v[8:11]
	v_mfma_f32_16x16x4_f32 v[8:11], v68, v60, v[8:11]
	v_mfma_f32_16x16x4_f32 v[8:11], v69, v61, v[8:11]
	v_mfma_f32_16x16x4_f32 v[8:11], v70, v62, v[8:11]
	v_mfma_f32_16x16x4_f32 v[8:11], v71, v63, v[8:11]
	global_load_dwordx4 v[28:31], v[4:5], off offset:704
	ds_read_b128 v[56:59], v148 offset:5120
	ds_read_b128 v[60:63], v148 offset:5136
	s_waitcnt vmcnt(7)
	v_lshlrev_b32_e32 v64, 16, v32
	v_and_b32_e32 v65, 0xffff0000, v32
	v_lshlrev_b32_e32 v66, 16, v33
	v_and_b32_e32 v67, 0xffff0000, v33
	v_lshlrev_b32_e32 v68, 16, v34
	v_and_b32_e32 v69, 0xffff0000, v34
	v_lshlrev_b32_e32 v70, 16, v35
	v_and_b32_e32 v71, 0xffff0000, v35
	s_waitcnt lgkmcnt(2)
	v_mfma_f32_16x16x4_f32 v[8:11], v64, v48, v[8:11]
	v_mfma_f32_16x16x4_f32 v[8:11], v65, v49, v[8:11]
	v_mfma_f32_16x16x4_f32 v[8:11], v66, v50, v[8:11]
	v_mfma_f32_16x16x4_f32 v[8:11], v67, v51, v[8:11]
	v_mfma_f32_16x16x4_f32 v[8:11], v68, v52, v[8:11]
	v_mfma_f32_16x16x4_f32 v[8:11], v69, v53, v[8:11]
	v_mfma_f32_16x16x4_f32 v[8:11], v70, v54, v[8:11]
	v_mfma_f32_16x16x4_f32 v[8:11], v71, v55, v[8:11]
	global_load_dwordx4 v[32:35], v[4:5], off offset:768
	ds_read_b128 v[48:51], v148 offset:6144
	ds_read_b128 v[52:55], v148 offset:6160
	s_waitcnt vmcnt(7)
	v_lshlrev_b32_e32 v64, 16, v36
	v_and_b32_e32 v65, 0xffff0000, v36
	v_lshlrev_b32_e32 v66, 16, v37
	v_and_b32_e32 v67, 0xffff0000, v37
	v_lshlrev_b32_e32 v68, 16, v38
	v_and_b32_e32 v69, 0xffff0000, v38
	v_lshlrev_b32_e32 v70, 16, v39
	v_and_b32_e32 v71, 0xffff0000, v39
	s_waitcnt lgkmcnt(2)
	v_mfma_f32_16x16x4_f32 v[8:11], v64, v56, v[8:11]
	v_mfma_f32_16x16x4_f32 v[8:11], v65, v57, v[8:11]
	v_mfma_f32_16x16x4_f32 v[8:11], v66, v58, v[8:11]
	v_mfma_f32_16x16x4_f32 v[8:11], v67, v59, v[8:11]
	v_mfma_f32_16x16x4_f32 v[8:11], v68, v60, v[8:11]
	v_mfma_f32_16x16x4_f32 v[8:11], v69, v61, v[8:11]
	v_mfma_f32_16x16x4_f32 v[8:11], v70, v62, v[8:11]
	v_mfma_f32_16x16x4_f32 v[8:11], v71, v63, v[8:11]
	global_load_dwordx4 v[36:39], v[4:5], off offset:832
	ds_read_b128 v[56:59], v148 offset:7168
	ds_read_b128 v[60:63], v148 offset:7184
	s_waitcnt vmcnt(7)
	v_lshlrev_b32_e32 v64, 16, v40
	v_and_b32_e32 v65, 0xffff0000, v40
	v_lshlrev_b32_e32 v66, 16, v41
	v_and_b32_e32 v67, 0xffff0000, v41
	v_lshlrev_b32_e32 v68, 16, v42
	v_and_b32_e32 v69, 0xffff0000, v42
	v_lshlrev_b32_e32 v70, 16, v43
	v_and_b32_e32 v71, 0xffff0000, v43
	s_waitcnt lgkmcnt(2)
	v_mfma_f32_16x16x4_f32 v[8:11], v64, v48, v[8:11]
	v_mfma_f32_16x16x4_f32 v[8:11], v65, v49, v[8:11]
	v_mfma_f32_16x16x4_f32 v[8:11], v66, v50, v[8:11]
	v_mfma_f32_16x16x4_f32 v[8:11], v67, v51, v[8:11]
	v_mfma_f32_16x16x4_f32 v[8:11], v68, v52, v[8:11]
	v_mfma_f32_16x16x4_f32 v[8:11], v69, v53, v[8:11]
	v_mfma_f32_16x16x4_f32 v[8:11], v70, v54, v[8:11]
	v_mfma_f32_16x16x4_f32 v[8:11], v71, v55, v[8:11]
	global_load_dwordx4 v[40:43], v[4:5], off offset:896
	ds_read_b128 v[48:51], v148 offset:8192
	ds_read_b128 v[52:55], v148 offset:8208
	s_waitcnt vmcnt(7)
	v_lshlrev_b32_e32 v64, 16, v44
	v_and_b32_e32 v65, 0xffff0000, v44
	v_lshlrev_b32_e32 v66, 16, v45
	v_and_b32_e32 v67, 0xffff0000, v45
	v_lshlrev_b32_e32 v68, 16, v46
	v_and_b32_e32 v69, 0xffff0000, v46
	v_lshlrev_b32_e32 v70, 16, v47
	v_and_b32_e32 v71, 0xffff0000, v47
	s_waitcnt lgkmcnt(2)
	v_mfma_f32_16x16x4_f32 v[8:11], v64, v56, v[8:11]
	v_mfma_f32_16x16x4_f32 v[8:11], v65, v57, v[8:11]
	v_mfma_f32_16x16x4_f32 v[8:11], v66, v58, v[8:11]
	v_mfma_f32_16x16x4_f32 v[8:11], v67, v59, v[8:11]
	v_mfma_f32_16x16x4_f32 v[8:11], v68, v60, v[8:11]
	v_mfma_f32_16x16x4_f32 v[8:11], v69, v61, v[8:11]
	v_mfma_f32_16x16x4_f32 v[8:11], v70, v62, v[8:11]
	v_mfma_f32_16x16x4_f32 v[8:11], v71, v63, v[8:11]
	global_load_dwordx4 v[44:47], v[4:5], off offset:960
	ds_read_b128 v[56:59], v148 offset:9216
	ds_read_b128 v[60:63], v148 offset:9232
	s_waitcnt vmcnt(7)
	v_lshlrev_b32_e32 v64, 16, v16
	v_and_b32_e32 v65, 0xffff0000, v16
	v_lshlrev_b32_e32 v66, 16, v17
	v_and_b32_e32 v67, 0xffff0000, v17
	v_lshlrev_b32_e32 v68, 16, v18
	v_and_b32_e32 v69, 0xffff0000, v18
	v_lshlrev_b32_e32 v70, 16, v19
	v_and_b32_e32 v71, 0xffff0000, v19
	s_waitcnt lgkmcnt(2)
; __device__ __forceinline__ float bf2f(bfu h) { return __uint_as_float(((unsigned)h) << 16); }
; #define SHX(v, m) shx_((v), (m), lane)
; __device__ void ba_item(const Params& p, int L, int rp) {
;     ...
;       _Pragma("unroll") for (int e = 0; e < 8; ++e) { hf[e] = bf2f((bfu)h0[u][e]); hf[8 + e] = bf2f((bfu)h1[u][e]); }
;       float a[8];
;       _Pragma("unroll") for (int j = 0; j < 8; ++j) {
;         float s = 0.f;
;         _Pragma("unroll") for (int e4 = 0; e4 < 4; ++e4) _Pragma("unroll") for (int e = 0; e < 4; ++e) s += hf[e4 * 4 + e] * wr_[j][e4][e];
;         _Pragma("unroll") for (int o = 32; o >= 1; o >>= 1) s += SHX(s, o);
;         a[j] = s;
;       }
	v_mfma_f32_16x16x4_f32 v[8:11], v64, v48, v[8:11]
	v_mfma_f32_16x16x4_f32 v[8:11], v65, v49, v[8:11]
	v_mfma_f32_16x16x4_f32 v[8:11], v66, v50, v[8:11]
	v_mfma_f32_16x16x4_f32 v[8:11], v67, v51, v[8:11]
	v_mfma_f32_16x16x4_f32 v[8:11], v68, v52, v[8:11]
	v_mfma_f32_16x16x4_f32 v[8:11], v69, v53, v[8:11]
	v_mfma_f32_16x16x4_f32 v[8:11], v70, v54, v[8:11]
	v_mfma_f32_16x16x4_f32 v[8:11], v71, v55, v[8:11]
	global_load_dwordx4 v[16:19], v[4:5], off offset:1024
	ds_read_b128 v[48:51], v148 offset:10240
	ds_read_b128 v[52:55], v148 offset:10256
	s_waitcnt vmcnt(7)
	v_lshlrev_b32_e32 v64, 16, v20
	v_and_b32_e32 v65, 0xffff0000, v20
	v_lshlrev_b32_e32 v66, 16, v21
	v_and_b32_e32 v67, 0xffff0000, v21
	v_lshlrev_b32_e32 v68, 16, v22
	v_and_b32_e32 v69, 0xffff0000, v22
	v_lshlrev_b32_e32 v70, 16, v23
	v_and_b32_e32 v71, 0xffff0000, v23
	s_waitcnt lgkmcnt(2)
	v_mfma_f32_16x16x4_f32 v[8:11], v64, v56, v[8:11]
	v_mfma_f32_16x16x4_f32 v[8:11], v65, v57, v[8:11]
	v_mfma_f32_16x16x4_f32 v[8:11], v66, v58, v[8:11]
	v_mfma_f32_16x16x4_f32 v[8:11], v67, v59, v[8:11]
	v_mfma_f32_16x16x4_f32 v[8:11], v68, v60, v[8:11]
	v_mfma_f32_16x16x4_f32 v[8:11], v69, v61, v[8:11]
	v_mfma_f32_16x16x4_f32 v[8:11], v70, v62, v[8:11]
	v_mfma_f32_16x16x4_f32 v[8:11], v71, v63, v[8:11]
	global_load_dwordx4 v[20:23], v[4:5], off offset:1088
	ds_read_b128 v[56:59], v148 offset:11264
	ds_read_b128 v[60:63], v148 offset:11280
	s_waitcnt vmcnt(7)
	v_lshlrev_b32_e32 v64, 16, v24
	v_and_b32_e32 v65, 0xffff0000, v24
	v_lshlrev_b32_e32 v66, 16, v25
	v_and_b32_e32 v67, 0xffff0000, v25
	v_lshlrev_b32_e32 v68, 16, v26
	v_and_b32_e32 v69, 0xffff0000, v26
	v_lshlrev_b32_e32 v70, 16, v27
	v_and_b32_e32 v71, 0xffff0000, v27
	s_waitcnt lgkmcnt(2)
	v_mfma_f32_16x16x4_f32 v[8:11], v64, v48, v[8:11]
	v_mfma_f32_16x16x4_f32 v[8:11], v65, v49, v[8:11]
	v_mfma_f32_16x16x4_f32 v[8:11], v66, v50, v[8:11]
	v_mfma_f32_16x16x4_f32 v[8:11], v67, v51, v[8:11]
	v_mfma_f32_16x16x4_f32 v[8:11], v68, v52, v[8:11]
	v_mfma_f32_16x16x4_f32 v[8:11], v69, v53, v[8:11]
	v_mfma_f32_16x16x4_f32 v[8:11], v70, v54, v[8:11]
	v_mfma_f32_16x16x4_f32 v[8:11], v71, v55, v[8:11]
	global_load_dwordx4 v[24:27], v[4:5], off offset:1152
	ds_read_b128 v[48:51], v148 offset:12288
	ds_read_b128 v[52:55], v148 offset:12304
	s_waitcnt vmcnt(7)
	v_lshlrev_b32_e32 v64, 16, v28
	v_and_b32_e32 v65, 0xffff0000, v28
	v_lshlrev_b32_e32 v66, 16, v29
	v_and_b32_e32 v67, 0xffff0000, v29
	v_lshlrev_b32_e32 v68, 16, v30
	v_and_b32_e32 v69, 0xffff0000, v30
	v_lshlrev_b32_e32 v70, 16, v31
	v_and_b32_e32 v71, 0xffff0000, v31
	s_waitcnt lgkmcnt(2)
	v_mfma_f32_16x16x4_f32 v[8:11], v64, v56, v[8:11]
	v_mfma_f32_16x16x4_f32 v[8:11], v65, v57, v[8:11]
	v_mfma_f32_16x16x4_f32 v[8:11], v66, v58, v[8:11]
	v_mfma_f32_16x16x4_f32 v[8:11], v67, v59, v[8:11]
	v_mfma_f32_16x16x4_f32 v[8:11], v68, v60, v[8:11]
	v_mfma_f32_16x16x4_f32 v[8:11], v69, v61, v[8:11]
	v_mfma_f32_16x16x4_f32 v[8:11], v70, v62, v[8:11]
	v_mfma_f32_16x16x4_f32 v[8:11], v71, v63, v[8:11]
	global_load_dwordx4 v[28:31], v[4:5], off offset:1216
	ds_read_b128 v[56:59], v148 offset:13312
	ds_read_b128 v[60:63], v148 offset:13328
	s_waitcnt vmcnt(7)
	v_lshlrev_b32_e32 v64, 16, v32
	v_and_b32_e32 v65, 0xffff0000, v32
	v_lshlrev_b32_e32 v66, 16, v33
	v_and_b32_e32 v67, 0xffff0000, v33
	v_lshlrev_b32_e32 v68, 16, v34
	v_and_b32_e32 v69, 0xffff0000, v34
	v_lshlrev_b32_e32 v70, 16, v35
	v_and_b32_e32 v71, 0xffff0000, v35
	s_waitcnt lgkmcnt(2)
	v_mfma_f32_16x16x4_f32 v[8:11], v64, v48, v[8:11]
	v_mfma_f32_16x16x4_f32 v[8:11], v65, v49, v[8:11]
	v_mfma_f32_16x16x4_f32 v[8:11], v66, v50, v[8:11]
	v_mfma_f32_16x16x4_f32 v[8:11], v67, v51, v[8:11]
	v_mfma_f32_16x16x4_f32 v[8:11], v68, v52, v[8:11]
	v_mfma_f32_16x16x4_f32 v[8:11], v69, v53, v[8:11]
	v_mfma_f32_16x16x4_f32 v[8:11], v70, v54, v[8:11]
	v_mfma_f32_16x16x4_f32 v[8:11], v71, v55, v[8:11]
	global_load_dwordx4 v[32:35], v[4:5], off offset:1280
	ds_read_b128 v[48:51], v148 offset:14336
	ds_read_b128 v[52:55], v148 offset:14352
	s_waitcnt vmcnt(7)
	v_lshlrev_b32_e32 v64, 16, v36
	v_and_b32_e32 v65, 0xffff0000, v36
	v_lshlrev_b32_e32 v66, 16, v37
	v_and_b32_e32 v67, 0xffff0000, v37
	v_lshlrev_b32_e32 v68, 16, v38
	v_and_b32_e32 v69, 0xffff0000, v38
	v_lshlrev_b32_e32 v70, 16, v39
	v_and_b32_e32 v71, 0xffff0000, v39
	s_waitcnt lgkmcnt(2)
	v_mfma_f32_16x16x4_f32 v[8:11], v64, v56, v[8:11]
	v_mfma_f32_16x16x4_f32 v[8:11], v65, v57, v[8:11]
	v_mfma_f32_16x16x4_f32 v[8:11], v66, v58, v[8:11]
	v_mfma_f32_16x16x4_f32 v[8:11], v67, v59, v[8:11]
	v_mfma_f32_16x16x4_f32 v[8:11], v68, v60, v[8:11]
	v_mfma_f32_16x16x4_f32 v[8:11], v69, v61, v[8:11]
	v_mfma_f32_16x16x4_f32 v[8:11], v70, v62, v[8:11]
	v_mfma_f32_16x16x4_f32 v[8:11], v71, v63, v[8:11]
	global_load_dwordx4 v[36:39], v[4:5], off offset:1344
	ds_read_b128 v[56:59], v148 offset:15360
	ds_read_b128 v[60:63], v148 offset:15376
	s_waitcnt vmcnt(7)
	v_lshlrev_b32_e32 v64, 16, v40
	v_and_b32_e32 v65, 0xffff0000, v40
	v_lshlrev_b32_e32 v66, 16, v41
	v_and_b32_e32 v67, 0xffff0000, v41
	v_lshlrev_b32_e32 v68, 16, v42
	v_and_b32_e32 v69, 0xffff0000, v42
	v_lshlrev_b32_e32 v70, 16, v43
	v_and_b32_e32 v71, 0xffff0000, v43
	s_waitcnt lgkmcnt(2)
	v_mfma_f32_16x16x4_f32 v[8:11], v64, v48, v[8:11]
	v_mfma_f32_16x16x4_f32 v[8:11], v65, v49, v[8:11]
	v_mfma_f32_16x16x4_f32 v[8:11], v66, v50, v[8:11]
	v_mfma_f32_16x16x4_f32 v[8:11], v67, v51, v[8:11]
	v_mfma_f32_16x16x4_f32 v[8:11], v68, v52, v[8:11]
	v_mfma_f32_16x16x4_f32 v[8:11], v69, v53, v[8:11]
	v_mfma_f32_16x16x4_f32 v[8:11], v70, v54, v[8:11]
	v_mfma_f32_16x16x4_f32 v[8:11], v71, v55, v[8:11]
	global_load_dwordx4 v[40:43], v[4:5], off offset:1408
	ds_read_b128 v[48:51], v148 offset:16384
	ds_read_b128 v[52:55], v148 offset:16400
	s_waitcnt vmcnt(7)
; __device__ __forceinline__ float bf2f(bfu h) { return __uint_as_float(((unsigned)h) << 16); }
; #define SHX(v, m) shx_((v), (m), lane)
; __device__ void ba_item(const Params& p, int L, int rp) {
;     ...
;       _Pragma("unroll") for (int e = 0; e < 8; ++e) { hf[e] = bf2f((bfu)h0[u][e]); hf[8 + e] = bf2f((bfu)h1[u][e]); }
;       float a[8];
;       _Pragma("unroll") for (int j = 0; j < 8; ++j) {
;         float s = 0.f;
;         _Pragma("unroll") for (int e4 = 0; e4 < 4; ++e4) _Pragma("unroll") for (int e = 0; e < 4; ++e) s += hf[e4 * 4 + e] * wr_[j][e4][e];
;         _Pragma("unroll") for (int o = 32; o >= 1; o >>= 1) s += SHX(s, o);
;         a[j] = s;
;       }
	v_lshlrev_b32_e32 v64, 16, v44
	v_and_b32_e32 v65, 0xffff0000, v44
	v_lshlrev_b32_e32 v66, 16, v45
	v_and_b32_e32 v67, 0xffff0000, v45
	v_lshlrev_b32_e32 v68, 16, v46
	v_and_b32_e32 v69, 0xffff0000, v46
	v_lshlrev_b32_e32 v70, 16, v47
	v_and_b32_e32 v71, 0xffff0000, v47
	s_waitcnt lgkmcnt(2)
	v_mfma_f32_16x16x4_f32 v[8:11], v64, v56, v[8:11]
	v_mfma_f32_16x16x4_f32 v[8:11], v65, v57, v[8:11]
	v_mfma_f32_16x16x4_f32 v[8:11], v66, v58, v[8:11]
	v_mfma_f32_16x16x4_f32 v[8:11], v67, v59, v[8:11]
	v_mfma_f32_16x16x4_f32 v[8:11], v68, v60, v[8:11]
	v_mfma_f32_16x16x4_f32 v[8:11], v69, v61, v[8:11]
	v_mfma_f32_16x16x4_f32 v[8:11], v70, v62, v[8:11]
	v_mfma_f32_16x16x4_f32 v[8:11], v71, v63, v[8:11]
	global_load_dwordx4 v[44:47], v[4:5], off offset:1472
	ds_read_b128 v[56:59], v148 offset:17408
	ds_read_b128 v[60:63], v148 offset:17424
	s_waitcnt vmcnt(7)
	v_lshlrev_b32_e32 v64, 16, v16
	v_and_b32_e32 v65, 0xffff0000, v16
	v_lshlrev_b32_e32 v66, 16, v17
	v_and_b32_e32 v67, 0xffff0000, v17
	v_lshlrev_b32_e32 v68, 16, v18
	v_and_b32_e32 v69, 0xffff0000, v18
	v_lshlrev_b32_e32 v70, 16, v19
	v_and_b32_e32 v71, 0xffff0000, v19
	s_waitcnt lgkmcnt(2)
	v_mfma_f32_16x16x4_f32 v[8:11], v64, v48, v[8:11]
	v_mfma_f32_16x16x4_f32 v[8:11], v65, v49, v[8:11]
	v_mfma_f32_16x16x4_f32 v[8:11], v66, v50, v[8:11]
	v_mfma_f32_16x16x4_f32 v[8:11], v67, v51, v[8:11]
	v_mfma_f32_16x16x4_f32 v[8:11], v68, v52, v[8:11]
	v_mfma_f32_16x16x4_f32 v[8:11], v69, v53, v[8:11]
	v_mfma_f32_16x16x4_f32 v[8:11], v70, v54, v[8:11]
	v_mfma_f32_16x16x4_f32 v[8:11], v71, v55, v[8:11]
	global_load_dwordx4 v[16:19], v[4:5], off offset:1536
	ds_read_b128 v[48:51], v148 offset:18432
	ds_read_b128 v[52:55], v148 offset:18448
	s_waitcnt vmcnt(7)
	v_lshlrev_b32_e32 v64, 16, v20
	v_and_b32_e32 v65, 0xffff0000, v20
	v_lshlrev_b32_e32 v66, 16, v21
	v_and_b32_e32 v67, 0xffff0000, v21
	v_lshlrev_b32_e32 v68, 16, v22
	v_and_b32_e32 v69, 0xffff0000, v22
	v_lshlrev_b32_e32 v70, 16, v23
	v_and_b32_e32 v71, 0xffff0000, v23
	s_waitcnt lgkmcnt(2)
	v_mfma_f32_16x16x4_f32 v[8:11], v64, v56, v[8:11]
	v_mfma_f32_16x16x4_f32 v[8:11], v65, v57, v[8:11]
	v_mfma_f32_16x16x4_f32 v[8:11], v66, v58, v[8:11]
	v_mfma_f32_16x16x4_f32 v[8:11], v67, v59, v[8:11]
	v_mfma_f32_16x16x4_f32 v[8:11], v68, v60, v[8:11]
	v_mfma_f32_16x16x4_f32 v[8:11], v69, v61, v[8:11]
	v_mfma_f32_16x16x4_f32 v[8:11], v70, v62, v[8:11]
	v_mfma_f32_16x16x4_f32 v[8:11], v71, v63, v[8:11]
	global_load_dwordx4 v[20:23], v[4:5], off offset:1600
	ds_read_b128 v[56:59], v148 offset:19456
	ds_read_b128 v[60:63], v148 offset:19472
	s_waitcnt vmcnt(7)
	v_lshlrev_b32_e32 v64, 16, v24
	v_and_b32_e32 v65, 0xffff0000, v24
	v_lshlrev_b32_e32 v66, 16, v25
	v_and_b32_e32 v67, 0xffff0000, v25
	v_lshlrev_b32_e32 v68, 16, v26
	v_and_b32_e32 v69, 0xffff0000, v26
	v_lshlrev_b32_e32 v70, 16, v27
	v_and_b32_e32 v71, 0xffff0000, v27
	s_waitcnt lgkmcnt(2)
	v_mfma_f32_16x16x4_f32 v[8:11], v64, v48, v[8:11]
	v_mfma_f32_16x16x4_f32 v[8:11], v65, v49, v[8:11]
	v_mfma_f32_16x16x4_f32 v[8:11], v66, v50, v[8:11]
	v_mfma_f32_16x16x4_f32 v[8:11], v67, v51, v[8:11]
	v_mfma_f32_16x16x4_f32 v[8:11], v68, v52, v[8:11]
	v_mfma_f32_16x16x4_f32 v[8:11], v69, v53, v[8:11]
	v_mfma_f32_16x16x4_f32 v[8:11], v70, v54, v[8:11]
	v_mfma_f32_16x16x4_f32 v[8:11], v71, v55, v[8:11]
	global_load_dwordx4 v[24:27], v[4:5], off offset:1664
	ds_read_b128 v[48:51], v148 offset:20480
	ds_read_b128 v[52:55], v148 offset:20496
	s_waitcnt vmcnt(7)
	v_lshlrev_b32_e32 v64, 16, v28
	v_and_b32_e32 v65, 0xffff0000, v28
	v_lshlrev_b32_e32 v66, 16, v29
	v_and_b32_e32 v67, 0xffff0000, v29
	v_lshlrev_b32_e32 v68, 16, v30
	v_and_b32_e32 v69, 0xffff0000, v30
	v_lshlrev_b32_e32 v70, 16, v31
	v_and_b32_e32 v71, 0xffff0000, v31
	s_waitcnt lgkmcnt(2)
	v_mfma_f32_16x16x4_f32 v[8:11], v64, v56, v[8:11]
	v_mfma_f32_16x16x4_f32 v[8:11], v65, v57, v[8:11]
	v_mfma_f32_16x16x4_f32 v[8:11], v66, v58, v[8:11]
	v_mfma_f32_16x16x4_f32 v[8:11], v67, v59, v[8:11]
	v_mfma_f32_16x16x4_f32 v[8:11], v68, v60, v[8:11]
	v_mfma_f32_16x16x4_f32 v[8:11], v69, v61, v[8:11]
	v_mfma_f32_16x16x4_f32 v[8:11], v70, v62, v[8:11]
	v_mfma_f32_16x16x4_f32 v[8:11], v71, v63, v[8:11]
	global_load_dwordx4 v[28:31], v[4:5], off offset:1728
	ds_read_b128 v[56:59], v148 offset:21504
	ds_read_b128 v[60:63], v148 offset:21520
	s_waitcnt vmcnt(7)
	v_lshlrev_b32_e32 v64, 16, v32
	v_and_b32_e32 v65, 0xffff0000, v32
	v_lshlrev_b32_e32 v66, 16, v33
	v_and_b32_e32 v67, 0xffff0000, v33
	v_lshlrev_b32_e32 v68, 16, v34
	v_and_b32_e32 v69, 0xffff0000, v34
	v_lshlrev_b32_e32 v70, 16, v35
	v_and_b32_e32 v71, 0xffff0000, v35
	s_waitcnt lgkmcnt(2)
	v_mfma_f32_16x16x4_f32 v[8:11], v64, v48, v[8:11]
	v_mfma_f32_16x16x4_f32 v[8:11], v65, v49, v[8:11]
	v_mfma_f32_16x16x4_f32 v[8:11], v66, v50, v[8:11]
	v_mfma_f32_16x16x4_f32 v[8:11], v67, v51, v[8:11]
	v_mfma_f32_16x16x4_f32 v[8:11], v68, v52, v[8:11]
	v_mfma_f32_16x16x4_f32 v[8:11], v69, v53, v[8:11]
	v_mfma_f32_16x16x4_f32 v[8:11], v70, v54, v[8:11]
	v_mfma_f32_16x16x4_f32 v[8:11], v71, v55, v[8:11]
	global_load_dwordx4 v[32:35], v[4:5], off offset:1792
	ds_read_b128 v[48:51], v148 offset:22528
	ds_read_b128 v[52:55], v148 offset:22544
	s_waitcnt vmcnt(7)
	v_lshlrev_b32_e32 v64, 16, v36
	v_and_b32_e32 v65, 0xffff0000, v36
	v_lshlrev_b32_e32 v66, 16, v37
	v_and_b32_e32 v67, 0xffff0000, v37
	v_lshlrev_b32_e32 v68, 16, v38
	v_and_b32_e32 v69, 0xffff0000, v38
	v_lshlrev_b32_e32 v70, 16, v39
	v_and_b32_e32 v71, 0xffff0000, v39
	s_waitcnt lgkmcnt(2)
; #define SHX(v, m) shx_((v), (m), lane)
; __device__ void ba_item(const Params& p, int L, int rp) {
;     ...
;       _Pragma("unroll") for (int j = 0; j < 8; ++j) {
;         float s = 0.f;
;         _Pragma("unroll") for (int e4 = 0; e4 < 4; ++e4) _Pragma("unroll") for (int e = 0; e < 4; ++e) s += hf[e4 * 4 + e] * wr_[j][e4][e];
;         _Pragma("unroll") for (int o = 32; o >= 1; o >>= 1) s += SHX(s, o);
;         a[j] = s;
;       }
	v_mfma_f32_16x16x4_f32 v[8:11], v64, v56, v[8:11]
	v_mfma_f32_16x16x4_f32 v[8:11], v65, v57, v[8:11]
	v_mfma_f32_16x16x4_f32 v[8:11], v66, v58, v[8:11]
	v_mfma_f32_16x16x4_f32 v[8:11], v67, v59, v[8:11]
	v_mfma_f32_16x16x4_f32 v[8:11], v68, v60, v[8:11]
	v_mfma_f32_16x16x4_f32 v[8:11], v69, v61, v[8:11]
	v_mfma_f32_16x16x4_f32 v[8:11], v70, v62, v[8:11]
	v_mfma_f32_16x16x4_f32 v[8:11], v71, v63, v[8:11]
	global_load_dwordx4 v[36:39], v[4:5], off offset:1856
	ds_read_b128 v[56:59], v148 offset:23552
	ds_read_b128 v[60:63], v148 offset:23568
	s_waitcnt vmcnt(7)
	v_lshlrev_b32_e32 v64, 16, v40
	v_and_b32_e32 v65, 0xffff0000, v40
	v_lshlrev_b32_e32 v66, 16, v41
	v_and_b32_e32 v67, 0xffff0000, v41
	v_lshlrev_b32_e32 v68, 16, v42
	v_and_b32_e32 v69, 0xffff0000, v42
	v_lshlrev_b32_e32 v70, 16, v43
	v_and_b32_e32 v71, 0xffff0000, v43
	s_waitcnt lgkmcnt(2)
	v_mfma_f32_16x16x4_f32 v[8:11], v64, v48, v[8:11]
	v_mfma_f32_16x16x4_f32 v[8:11], v65, v49, v[8:11]
	v_mfma_f32_16x16x4_f32 v[8:11], v66, v50, v[8:11]
	v_mfma_f32_16x16x4_f32 v[8:11], v67, v51, v[8:11]
	v_mfma_f32_16x16x4_f32 v[8:11], v68, v52, v[8:11]
	v_mfma_f32_16x16x4_f32 v[8:11], v69, v53, v[8:11]
	v_mfma_f32_16x16x4_f32 v[8:11], v70, v54, v[8:11]
	v_mfma_f32_16x16x4_f32 v[8:11], v71, v55, v[8:11]
	global_load_dwordx4 v[40:43], v[4:5], off offset:1920
	ds_read_b128 v[48:51], v148 offset:24576
	ds_read_b128 v[52:55], v148 offset:24592
	s_waitcnt vmcnt(7)
	v_lshlrev_b32_e32 v64, 16, v44
	v_and_b32_e32 v65, 0xffff0000, v44
	v_lshlrev_b32_e32 v66, 16, v45
	v_and_b32_e32 v67, 0xffff0000, v45
	v_lshlrev_b32_e32 v68, 16, v46
	v_and_b32_e32 v69, 0xffff0000, v46
	v_lshlrev_b32_e32 v70, 16, v47
	v_and_b32_e32 v71, 0xffff0000, v47
	s_waitcnt lgkmcnt(2)
	v_mfma_f32_16x16x4_f32 v[8:11], v64, v56, v[8:11]
	v_mfma_f32_16x16x4_f32 v[8:11], v65, v57, v[8:11]
	v_mfma_f32_16x16x4_f32 v[8:11], v66, v58, v[8:11]
	v_mfma_f32_16x16x4_f32 v[8:11], v67, v59, v[8:11]
	v_mfma_f32_16x16x4_f32 v[8:11], v68, v60, v[8:11]
	v_mfma_f32_16x16x4_f32 v[8:11], v69, v61, v[8:11]
	v_mfma_f32_16x16x4_f32 v[8:11], v70, v62, v[8:11]
	v_mfma_f32_16x16x4_f32 v[8:11], v71, v63, v[8:11]
	global_load_dwordx4 v[44:47], v[4:5], off offset:1984
	ds_read_b128 v[56:59], v148 offset:25600
	ds_read_b128 v[60:63], v148 offset:25616
	s_waitcnt vmcnt(7)
	v_lshlrev_b32_e32 v64, 16, v16
	v_and_b32_e32 v65, 0xffff0000, v16
	v_lshlrev_b32_e32 v66, 16, v17
	v_and_b32_e32 v67, 0xffff0000, v17
	v_lshlrev_b32_e32 v68, 16, v18
	v_and_b32_e32 v69, 0xffff0000, v18
	v_lshlrev_b32_e32 v70, 16, v19
	v_and_b32_e32 v71, 0xffff0000, v19
	s_waitcnt lgkmcnt(2)
	v_mfma_f32_16x16x4_f32 v[8:11], v64, v48, v[8:11]
	v_mfma_f32_16x16x4_f32 v[8:11], v65, v49, v[8:11]
	v_mfma_f32_16x16x4_f32 v[8:11], v66, v50, v[8:11]
	v_mfma_f32_16x16x4_f32 v[8:11], v67, v51, v[8:11]
	v_mfma_f32_16x16x4_f32 v[8:11], v68, v52, v[8:11]
	v_mfma_f32_16x16x4_f32 v[8:11], v69, v53, v[8:11]
	v_mfma_f32_16x16x4_f32 v[8:11], v70, v54, v[8:11]
	v_mfma_f32_16x16x4_f32 v[8:11], v71, v55, v[8:11]
	ds_read_b128 v[48:51], v148 offset:26624
	ds_read_b128 v[52:55], v148 offset:26640
	s_waitcnt vmcnt(6)
	v_lshlrev_b32_e32 v64, 16, v20
	v_and_b32_e32 v65, 0xffff0000, v20
	v_lshlrev_b32_e32 v66, 16, v21
	v_and_b32_e32 v67, 0xffff0000, v21
	v_lshlrev_b32_e32 v68, 16, v22
	v_and_b32_e32 v69, 0xffff0000, v22
	v_lshlrev_b32_e32 v70, 16, v23
	v_and_b32_e32 v71, 0xffff0000, v23
	s_waitcnt lgkmcnt(2)
	v_mfma_f32_16x16x4_f32 v[8:11], v64, v56, v[8:11]
	v_mfma_f32_16x16x4_f32 v[8:11], v65, v57, v[8:11]
	v_mfma_f32_16x16x4_f32 v[8:11], v66, v58, v[8:11]
	v_mfma_f32_16x16x4_f32 v[8:11], v67, v59, v[8:11]
	v_mfma_f32_16x16x4_f32 v[8:11], v68, v60, v[8:11]
	v_mfma_f32_16x16x4_f32 v[8:11], v69, v61, v[8:11]
	v_mfma_f32_16x16x4_f32 v[8:11], v70, v62, v[8:11]
	v_mfma_f32_16x16x4_f32 v[8:11], v71, v63, v[8:11]
	ds_read_b128 v[56:59], v148 offset:27648
	ds_read_b128 v[60:63], v148 offset:27664
	s_waitcnt vmcnt(5)
	v_lshlrev_b32_e32 v64, 16, v24
	v_and_b32_e32 v65, 0xffff0000, v24
	v_lshlrev_b32_e32 v66, 16, v25
	v_and_b32_e32 v67, 0xffff0000, v25
	v_lshlrev_b32_e32 v68, 16, v26
	v_and_b32_e32 v69, 0xffff0000, v26
	v_lshlrev_b32_e32 v70, 16, v27
	v_and_b32_e32 v71, 0xffff0000, v27
	s_waitcnt lgkmcnt(2)
	v_mfma_f32_16x16x4_f32 v[8:11], v64, v48, v[8:11]
	v_mfma_f32_16x16x4_f32 v[8:11], v65, v49, v[8:11]
	v_mfma_f32_16x16x4_f32 v[8:11], v66, v50, v[8:11]
	v_mfma_f32_16x16x4_f32 v[8:11], v67, v51, v[8:11]
	v_mfma_f32_16x16x4_f32 v[8:11], v68, v52, v[8:11]
	v_mfma_f32_16x16x4_f32 v[8:11], v69, v53, v[8:11]
	v_mfma_f32_16x16x4_f32 v[8:11], v70, v54, v[8:11]
	v_mfma_f32_16x16x4_f32 v[8:11], v71, v55, v[8:11]
	ds_read_b128 v[48:51], v148 offset:28672
	ds_read_b128 v[52:55], v148 offset:28688
	s_waitcnt vmcnt(4)
	v_lshlrev_b32_e32 v64, 16, v28
	v_and_b32_e32 v65, 0xffff0000, v28
	v_lshlrev_b32_e32 v66, 16, v29
	v_and_b32_e32 v67, 0xffff0000, v29
	v_lshlrev_b32_e32 v68, 16, v30
	v_and_b32_e32 v69, 0xffff0000, v30
	v_lshlrev_b32_e32 v70, 16, v31
	v_and_b32_e32 v71, 0xffff0000, v31
	s_waitcnt lgkmcnt(2)
	v_mfma_f32_16x16x4_f32 v[8:11], v64, v56, v[8:11]
	v_mfma_f32_16x16x4_f32 v[8:11], v65, v57, v[8:11]
	v_mfma_f32_16x16x4_f32 v[8:11], v66, v58, v[8:11]
	v_mfma_f32_16x16x4_f32 v[8:11], v67, v59, v[8:11]
	v_mfma_f32_16x16x4_f32 v[8:11], v68, v60, v[8:11]
	v_mfma_f32_16x16x4_f32 v[8:11], v69, v61, v[8:11]
	v_mfma_f32_16x16x4_f32 v[8:11], v70, v62, v[8:11]
	v_mfma_f32_16x16x4_f32 v[8:11], v71, v63, v[8:11]
	ds_read_b128 v[56:59], v148 offset:29696
	ds_read_b128 v[60:63], v148 offset:29712
	s_waitcnt vmcnt(3)
; #define SHX(v, m) shx_((v), (m), lane)
; __device__ void ba_item(const Params& p, int L, int rp) {
;     ...
;       _Pragma("unroll") for (int j = 0; j < 8; ++j) {
;         float s = 0.f;
;         _Pragma("unroll") for (int e4 = 0; e4 < 4; ++e4) _Pragma("unroll") for (int e = 0; e < 4; ++e) s += hf[e4 * 4 + e] * wr_[j][e4][e];
;         _Pragma("unroll") for (int o = 32; o >= 1; o >>= 1) s += SHX(s, o);
;         a[j] = s;
;       }
	v_lshlrev_b32_e32 v64, 16, v32
	v_and_b32_e32 v65, 0xffff0000, v32
	v_lshlrev_b32_e32 v66, 16, v33
	v_and_b32_e32 v67, 0xffff0000, v33
	v_lshlrev_b32_e32 v68, 16, v34
	v_and_b32_e32 v69, 0xffff0000, v34
	v_lshlrev_b32_e32 v70, 16, v35
	v_and_b32_e32 v71, 0xffff0000, v35
	s_waitcnt lgkmcnt(2)
	v_mfma_f32_16x16x4_f32 v[8:11], v64, v48, v[8:11]
	v_mfma_f32_16x16x4_f32 v[8:11], v65, v49, v[8:11]
	v_mfma_f32_16x16x4_f32 v[8:11], v66, v50, v[8:11]
	v_mfma_f32_16x16x4_f32 v[8:11], v67, v51, v[8:11]
	v_mfma_f32_16x16x4_f32 v[8:11], v68, v52, v[8:11]
	v_mfma_f32_16x16x4_f32 v[8:11], v69, v53, v[8:11]
	v_mfma_f32_16x16x4_f32 v[8:11], v70, v54, v[8:11]
	v_mfma_f32_16x16x4_f32 v[8:11], v71, v55, v[8:11]
	ds_read_b128 v[48:51], v148 offset:30720
	ds_read_b128 v[52:55], v148 offset:30736
	s_waitcnt vmcnt(2)
	v_lshlrev_b32_e32 v64, 16, v36
	v_and_b32_e32 v65, 0xffff0000, v36
	v_lshlrev_b32_e32 v66, 16, v37
	v_and_b32_e32 v67, 0xffff0000, v37
	v_lshlrev_b32_e32 v68, 16, v38
	v_and_b32_e32 v69, 0xffff0000, v38
	v_lshlrev_b32_e32 v70, 16, v39
	v_and_b32_e32 v71, 0xffff0000, v39
	s_waitcnt lgkmcnt(2)
	v_mfma_f32_16x16x4_f32 v[8:11], v64, v56, v[8:11]
	v_mfma_f32_16x16x4_f32 v[8:11], v65, v57, v[8:11]
	v_mfma_f32_16x16x4_f32 v[8:11], v66, v58, v[8:11]
	v_mfma_f32_16x16x4_f32 v[8:11], v67, v59, v[8:11]
	v_mfma_f32_16x16x4_f32 v[8:11], v68, v60, v[8:11]
	v_mfma_f32_16x16x4_f32 v[8:11], v69, v61, v[8:11]
	v_mfma_f32_16x16x4_f32 v[8:11], v70, v62, v[8:11]
	v_mfma_f32_16x16x4_f32 v[8:11], v71, v63, v[8:11]
	ds_read_b128 v[56:59], v148 offset:31744
	ds_read_b128 v[60:63], v148 offset:31760
	s_waitcnt vmcnt(1)
	v_lshlrev_b32_e32 v64, 16, v40
	v_and_b32_e32 v65, 0xffff0000, v40
	v_lshlrev_b32_e32 v66, 16, v41
	v_and_b32_e32 v67, 0xffff0000, v41
	v_lshlrev_b32_e32 v68, 16, v42
	v_and_b32_e32 v69, 0xffff0000, v42
	v_lshlrev_b32_e32 v70, 16, v43
	v_and_b32_e32 v71, 0xffff0000, v43
	s_waitcnt lgkmcnt(2)
	v_mfma_f32_16x16x4_f32 v[8:11], v64, v48, v[8:11]
	v_mfma_f32_16x16x4_f32 v[8:11], v65, v49, v[8:11]
	v_mfma_f32_16x16x4_f32 v[8:11], v66, v50, v[8:11]
	v_mfma_f32_16x16x4_f32 v[8:11], v67, v51, v[8:11]
	v_mfma_f32_16x16x4_f32 v[8:11], v68, v52, v[8:11]
	v_mfma_f32_16x16x4_f32 v[8:11], v69, v53, v[8:11]
	v_mfma_f32_16x16x4_f32 v[8:11], v70, v54, v[8:11]
	v_mfma_f32_16x16x4_f32 v[8:11], v71, v55, v[8:11]
	s_waitcnt vmcnt(0)
	v_lshlrev_b32_e32 v64, 16, v44
	v_and_b32_e32 v65, 0xffff0000, v44
	v_lshlrev_b32_e32 v66, 16, v45
	v_and_b32_e32 v67, 0xffff0000, v45
	v_lshlrev_b32_e32 v68, 16, v46
	v_and_b32_e32 v69, 0xffff0000, v46
	v_lshlrev_b32_e32 v70, 16, v47
	v_and_b32_e32 v71, 0xffff0000, v47
	s_waitcnt lgkmcnt(0)
; __device__ __forceinline__ float fexp(float x) { return __builtin_amdgcn_exp2f(x * 1.4426950408889634f); }
; __device__ __forceinline__ float flog(float x) { return __builtin_amdgcn_logf(x) * 0.6931471805599453f; }
; __device__ __forceinline__ float frsq(float x) { return __builtin_amdgcn_rsqf(x); }
; __device__ __forceinline__ float sigmoidf_(float x) { return frcp(1.0f + fexp(-x)); }
; #define SHX(v, m) shx_((v), (m), lane)
; __device__ void ba_item(const Params& p, int L, int rp) {
;     ...
;       _Pragma("unroll") for (int j = 0; j < 8; ++j) {
;         float s = 0.f;
;         _Pragma("unroll") for (int e4 = 0; e4 < 4; ++e4) _Pragma("unroll") for (int e = 0; e < 4; ++e) s += hf[e4 * 4 + e] * wr_[j][e4][e];
;         _Pragma("unroll") for (int o = 32; o >= 1; o >>= 1) s += SHX(s, o);
;         a[j] = s;
;       }
;       if (lane < 8) {
;         float s16 = 0.f;
;         _Pragma("unroll") for (int i = 0; i < 4; ++i) s16 += (ps[u][i][0] + ps[u][i][1]) + (ps[u][i][2] + ps[u][i][3]);
;         float rs = frsq(s16 * (1.0f / 1024.0f) + 1e-6f);
;         float v = 0.f;
;         _Pragma("unroll") for (int j = 0; j < 8; ++j) if (lane == j) v = a[j];
;         v *= rs;
;         float r;
;         if (lane < 4) r = sigmoidf_(v);
;         else {
;           int hh = lane - 4;
;           float z = v + p.dn_dt_bias[(L >> 1) * 4 + hh];
;           float sp = (z > 20.f) ? z : flog(1.0f + fexp(z));
;           r = -fexp(p.dn_a_log[(L >> 1) * 4 + hh]) * sp;
;         }
;         miscw[MF_BG + (long)row * 8 + lane] = r;
;       }
	v_mfma_f32_16x16x4_f32 v[8:11], v64, v56, v[8:11]
	v_mfma_f32_16x16x4_f32 v[8:11], v65, v57, v[8:11]
	v_mfma_f32_16x16x4_f32 v[8:11], v66, v58, v[8:11]
	v_mfma_f32_16x16x4_f32 v[8:11], v67, v59, v[8:11]
	v_mfma_f32_16x16x4_f32 v[8:11], v68, v60, v[8:11]
	v_mfma_f32_16x16x4_f32 v[8:11], v69, v61, v[8:11]
	v_mfma_f32_16x16x4_f32 v[8:11], v70, v62, v[8:11]
	v_mfma_f32_16x16x4_f32 v[8:11], v71, v63, v[8:11]
	v_cmp_gt_u32_e32 vcc, 8, v2
	s_and_saveexec_b64 s[12:13], vcc
	s_nop 4
	v_add_f32_e32 v72, v72, v73
	v_add_f32_e32 v74, v74, v75
	v_add_f32_e32 v72, v72, v74
	v_add_f32_e32 v76, v76, v77
	v_add_f32_e32 v78, v78, v79
	v_add_f32_e32 v76, v76, v78
	v_add_f32_e32 v80, v80, v81
	v_add_f32_e32 v82, v82, v83
	v_add_f32_e32 v80, v80, v82
	v_add_f32_e32 v84, v84, v85
	v_add_f32_e32 v86, v86, v87
	v_add_f32_e32 v84, v84, v86
	v_add_f32_e32 v72, 0, v72
	v_add_f32_e32 v72, v76, v72
	v_add_f32_e32 v72, v80, v72
	v_add_f32_e32 v72, v84, v72
	v_fmamk_f32 v72, v72, 0x3a800000, v201
	v_rsq_f32_e32 v72, v72
	s_nop 0
	v_mul_f32_e32 v144, v8, v72
	v_mul_f32_e32 v145, 0xbfb8aa3b, v144
	v_exp_f32_e32 v145, v145
	s_nop 0
	v_add_f32_e32 v145, 1.0, v145
	v_rcp_f32_e32 v145, v145
	v_add_f32_e32 v146, v144, v142
	v_mul_f32_e32 v147, 0x3fb8aa3b, v146
	v_exp_f32_e32 v147, v147
	v_cmp_lt_f32_e64 s[0:1], s57, v146
	v_add_f32_e32 v147, 1.0, v147
	v_log_f32_e32 v147, v147
	s_nop 0
	v_mul_f32_e32 v147, 0x3f317218, v147
	v_cndmask_b32_e64 v146, v147, v146, s[0:1]
	v_mul_f32_e32 v147, 0x3fb8aa3b, v143
	v_exp_f32_e32 v147, v147
	s_nop 0
	v_mul_f32_e64 v146, v146, -v147
	v_cmp_gt_u32_e64 s[0:1], 4, v138
	s_nop 1
	v_cndmask_b32_e64 v146, v146, v145, s[0:1]
	global_store_dword v[140:141], v146, off offset:0
	v_add_f32_e32 v88, v88, v89
	v_add_f32_e32 v90, v90, v91
	v_add_f32_e32 v88, v88, v90
	v_add_f32_e32 v92, v92, v93
	v_add_f32_e32 v94, v94, v95
	v_add_f32_e32 v92, v92, v94
	v_add_f32_e32 v96, v96, v97
	v_add_f32_e32 v98, v98, v99
	v_add_f32_e32 v96, v96, v98
	v_add_f32_e32 v100, v100, v101
	v_add_f32_e32 v102, v102, v103
	v_add_f32_e32 v100, v100, v102
	v_add_f32_e32 v88, 0, v88
	v_add_f32_e32 v88, v92, v88
	v_add_f32_e32 v88, v96, v88
	v_add_f32_e32 v88, v100, v88
	v_fmamk_f32 v88, v88, 0x3a800000, v201
	v_rsq_f32_e32 v88, v88
	s_nop 0
	v_mul_f32_e32 v144, v9, v88
	v_mul_f32_e32 v145, 0xbfb8aa3b, v144
	v_exp_f32_e32 v145, v145
	s_nop 0
	v_add_f32_e32 v145, 1.0, v145
	v_rcp_f32_e32 v145, v145
	v_add_f32_e32 v146, v144, v142
	v_mul_f32_e32 v147, 0x3fb8aa3b, v146
	v_exp_f32_e32 v147, v147
	v_cmp_lt_f32_e64 s[0:1], s57, v146
	v_add_f32_e32 v147, 1.0, v147
	v_log_f32_e32 v147, v147
	s_nop 0
	v_mul_f32_e32 v147, 0x3f317218, v147
	v_cndmask_b32_e64 v146, v147, v146, s[0:1]
	v_mul_f32_e32 v147, 0x3fb8aa3b, v143
	v_exp_f32_e32 v147, v147
	s_nop 0
	v_mul_f32_e64 v146, v146, -v147
	v_cmp_gt_u32_e64 s[0:1], 4, v138
	s_nop 1
	v_cndmask_b32_e64 v146, v146, v145, s[0:1]
	global_store_dword v[140:141], v146, off offset:32
	v_add_f32_e32 v104, v104, v105
	v_add_f32_e32 v106, v106, v107
	v_add_f32_e32 v104, v104, v106
	v_add_f32_e32 v108, v108, v109
	v_add_f32_e32 v110, v110, v111
	v_add_f32_e32 v108, v108, v110
	v_add_f32_e32 v112, v112, v113
	v_add_f32_e32 v114, v114, v115
	v_add_f32_e32 v112, v112, v114
	v_add_f32_e32 v116, v116, v117
	v_add_f32_e32 v118, v118, v119
	v_add_f32_e32 v116, v116, v118
	v_add_f32_e32 v104, 0, v104
	v_add_f32_e32 v104, v108, v104
	v_add_f32_e32 v104, v112, v104
	v_add_f32_e32 v104, v116, v104
	v_fmamk_f32 v104, v104, 0x3a800000, v201
	v_rsq_f32_e32 v104, v104
	s_nop 0
	v_mul_f32_e32 v144, v10, v104
	v_mul_f32_e32 v145, 0xbfb8aa3b, v144
	v_exp_f32_e32 v145, v145
	s_nop 0
	v_add_f32_e32 v145, 1.0, v145
	v_rcp_f32_e32 v145, v145
	v_add_f32_e32 v146, v144, v142
	v_mul_f32_e32 v147, 0x3fb8aa3b, v146
	v_exp_f32_e32 v147, v147
	v_cmp_lt_f32_e64 s[0:1], s57, v146
	v_add_f32_e32 v147, 1.0, v147
	v_log_f32_e32 v147, v147
	s_nop 0
	v_mul_f32_e32 v147, 0x3f317218, v147
	v_cndmask_b32_e64 v146, v147, v146, s[0:1]
	v_mul_f32_e32 v147, 0x3fb8aa3b, v143
	v_exp_f32_e32 v147, v147
	s_nop 0
	v_mul_f32_e64 v146, v146, -v147
	v_cmp_gt_u32_e64 s[0:1], 4, v138
	s_nop 1
	v_cndmask_b32_e64 v146, v146, v145, s[0:1]
	global_store_dword v[140:141], v146, off offset:64
	v_add_f32_e32 v120, v120, v121
	v_add_f32_e32 v122, v122, v123
	v_add_f32_e32 v120, v120, v122
	v_add_f32_e32 v124, v124, v125
	v_add_f32_e32 v126, v126, v127
	v_add_f32_e32 v124, v124, v126
	v_add_f32_e32 v128, v128, v129
	v_add_f32_e32 v130, v130, v131
	v_add_f32_e32 v128, v128, v130
	v_add_f32_e32 v132, v132, v133
	v_add_f32_e32 v134, v134, v135
	v_add_f32_e32 v132, v132, v134
	v_add_f32_e32 v120, 0, v120
	v_add_f32_e32 v120, v124, v120
	v_add_f32_e32 v120, v128, v120
	v_add_f32_e32 v120, v132, v120
	v_fmamk_f32 v120, v120, 0x3a800000, v201
	v_rsq_f32_e32 v120, v120
	s_nop 0
	v_mul_f32_e32 v144, v11, v120
	v_mul_f32_e32 v145, 0xbfb8aa3b, v144
	v_exp_f32_e32 v145, v145
	s_nop 0
	v_add_f32_e32 v145, 1.0, v145
	v_rcp_f32_e32 v145, v145
	v_add_f32_e32 v146, v144, v142
	v_mul_f32_e32 v147, 0x3fb8aa3b, v146
	v_exp_f32_e32 v147, v147
	v_cmp_lt_f32_e64 s[0:1], s57, v146
	v_add_f32_e32 v147, 1.0, v147
	v_log_f32_e32 v147, v147
	s_nop 0
	v_mul_f32_e32 v147, 0x3f317218, v147
	v_cndmask_b32_e64 v146, v147, v146, s[0:1]
	v_mul_f32_e32 v147, 0x3fb8aa3b, v143
	v_exp_f32_e32 v147, v147
	s_nop 0
	v_mul_f32_e64 v146, v146, -v147
	v_cmp_gt_u32_e64 s[0:1], 4, v138
	s_nop 1
	v_cndmask_b32_e64 v146, v146, v145, s[0:1]
	global_store_dword v[140:141], v146, off offset:96
	s_or_b64 exec, exec, s[12:13]
	s_barrier
	s_branch .LBB0_627
